# leading wave-half runs its hand-written GEMM epilogue before (not after) the align barrier, overlapping the trailing half's last MFMA block
# baseline (speedup 1.0000x reference)
;     __host__ __device__ __forceinline__ bool next(int i, Unit& uo) const {
;         if (ns == 8) {
;             const int L = i * G + c; Unit u;
;             if (L < 512) {
;                 int wgid = L; { const int q = 512 / NXCD, xcd = wgid % NXCD, off = wgid / NXCD; wgid = xcd * q + off; }
;                 const int nig = WGM * nN; const int gid = wgid / nig, fm = gid * WGM;
;                 u.pm = fm + ((wgid % nig) / nN); u.pn = (wgid % nig) % nN; u.kb = 0; u.nk = KT; u.part = 2;
;             } else {
;                 const int q = L - 512, t = q % 32, kp = q / 32;
;                 u.pm = 64 + t / 8; u.pn = t % 8; u.nk = KT / 8; u.kb = kp * u.nk; u.part = 16 + kp;
;             }
;             uo = u; return L < 768;
;         }
;         const int np = nwg * ns;
;         const int L = i * G + c; const bool ok = L < np;
;         int wgid = L; { const int q = np / NXCD, r = np % NXCD, xcd = wgid % NXCD, off = wgid / NXCD; wgid = (xcd < r ? xcd * (q + 1) : r * (q + 1) + (xcd - r) * q) + off; }
;         const int half = wgid >= nwg ? 1 : 0; wgid -= half * nwg;
;         const int nig = WGM * nN, gid = wgid / nig, fm = gid * WGM, gsz = (nM - fm) < WGM ? (nM - fm) : WGM;
;         Unit u; u.pm = fm + ((wgid % nig) % gsz); u.pn = (wgid % nig) / gsz; u.nk = KT / ns; u.kb = half * u.nk; u.part = ns == 2 ? half : 2;
; DI void run_gemm(LAS unsigned char* lds, const bf16* A, int lda, const bf16* Bt, int M, int N, int K, const EpiMode& E) {
;   pg8::Gemm g{A, Bt, M, N, K, lda}; pg8::StaticOrder S; S.init(M, N, K, (int)gridDim.x, (int)blockIdx.x, E.mode == EM_TAIL ? 8 : E.mode == EM_SPLIT ? 2 : 1);
.LBB0_452:
	s_and_b64 vcc, exec, s[6:7]
	s_cbranch_vccz .LBB0_944
	v_writelane_b32 v255, 0, 61
	v_writelane_b32 v255, 0, 62
	s_cmp_lg_u32 s71, 6
	v_writelane_b32 v255, s22, 37
	s_cselect_b64 s[72:73], -1, 0
	s_cmp_eq_u32 s71, 5
	v_writelane_b32 v255, s23, 38
	s_cselect_b64 s[6:7], -1, 0
	s_and_b64 s[0:1], s[6:7], exec
	v_readlane_b32 s2, v255, 30
	s_cselect_b32 s0, 2, 1
	s_ashr_i32 s1, s2, 31
	s_lshr_b32 s1, s1, 24
	s_add_i32 s1, s2, s1
	v_readlane_b32 s2, v255, 29
	s_ashr_i32 s29, s1, 8
	s_ashr_i32 s1, s2, 31
	s_lshr_b32 s1, s1, 24
	s_add_i32 s1, s2, s1
	s_ashr_i32 s21, s20, 31
	s_ashr_i32 s4, s1, 8
	s_lshr_b32 s1, s21, 26
	s_add_i32 s1, s20, s1
	v_mov_b32_e32 v12, v181
	s_mul_i32 s28, s29, s4
	s_ashr_i32 s87, s1, 6
	s_mov_b64 s[8:9], -1
	v_readfirstlane_b32 s1, v12
	s_and_b64 vcc, exec, s[72:73]
	s_cbranch_vccz .LBB0_459
	v_cndmask_b32_e64 v0, 0, 1, s[6:7]
	s_nop 0
	v_readfirstlane_b32 s2, v0
	s_lshl_b32 s2, s28, s2
	s_ashr_i32 s3, s2, 31
	s_lshr_b32 s3, s3, 29
	s_add_i32 s3, s2, s3
	s_ashr_i32 s10, s3, 3
	s_and_b32 s3, s3, -8
	s_sub_i32 s11, s2, s3
	s_add_i32 s5, s10, 1
	s_cmp_ge_i32 s70, s11
	s_cbranch_scc0 .LBB0_456
	s_sub_i32 s8, s70, s11
	s_mul_i32 s3, s5, s11
	s_mul_i32 s8, s8, s10
	s_add_i32 s3, s8, s3
	s_mov_b64 s[8:9], 0

; #define PG8_BAR __builtin_amdgcn_s_barrier()
; template <class Epi, class Sched, bool ALIGN_EPI = false, bool SP2 = false>
; __device__ __forceinline__ void gemm_phase(PG8_LAS unsigned char* lds, const Gemm g, const Sched& S, const Epi& E) {
;     ...
;         if constexpr (ALIGN_EPI) { if (wr == 0) PG8_BAR; }
;         if constexpr (!Epi::AFTER_DRAIN) { E(acc, cur, wr, wc, fr, fq); S.done(cur); }
.Lk_exit:
	s_cmp_eq_u32 s71, 0
	s_cbranch_scc1 .Lalign_defer
	s_cmp_eq_u32 s71, 2
	s_cbranch_scc1 .Lalign_defer
	s_cmp_eq_u32 s71, 6
	s_cbranch_scc1 .Lalign_defer
	s_and_b64 vcc, exec, s[18:19]
	s_cbranch_vccz .LBB0_490

; #define PG8_BAR __builtin_amdgcn_s_barrier()
; template <class Epi, class Sched, bool ALIGN_EPI = false, bool SP2 = false>
; __device__ __forceinline__ void gemm_phase(PG8_LAS unsigned char* lds, const Gemm g, const Sched& S, const Epi& E) {
;     ...
;         if constexpr (ALIGN_EPI) { if (wr == 0) PG8_BAR; }
;         if constexpr (!Epi::AFTER_DRAIN) { E(acc, cur, wr, wc, fr, fq); S.done(cur); }
.Lalign_defer:
	s_and_b64 vcc, exec, s[18:19]
	s_cbranch_vccz .LBB0_490
	v_writelane_b32 v255, 1, 61
	s_branch .LBB0_490

; #define PG8_BAR __builtin_amdgcn_s_barrier()
; DI u32x4 pack8(f32x4 a, f32x4 b) { u32x4 w; w.x = cvtpk(a.x, a.y); w.y = cvtpk(a.z, a.w); w.z = cvtpk(b.x, b.y); w.w = cvtpk(b.z, b.w); return w; }
; template <class Epi, class Sched, bool ALIGN_EPI = false, bool SP2 = false>
; __device__ __forceinline__ void gemm_phase(PG8_LAS unsigned char* lds, const Gemm g, const Sched& S, const Epi& E) {
;     ...
;         if constexpr (ALIGN_EPI) { if (wr == 0) PG8_BAR; }
;   template <int MODE> DI void store8(int row, int col, f32x4 v0, f32x4 v1, int part) const {
;     ...
;     } else if (MODE == EM_BF16) { *(u32x4*)(O + (size_t)row * ldc + col) = pack8(v0, v1); }
;     else if (MODE == EM_RELU2) {
;       f32x4 a = __builtin_elementwise_max(v0, (f32x4){0.f, 0.f, 0.f, 0.f}), b = __builtin_elementwise_max(v1, (f32x4){0.f, 0.f, 0.f, 0.f});
;       *(u32x4*)(O + (size_t)row * ldc + col) = pack8(a * a, b * b); }
.Lepi_plain_bd:
	v_cvt_pk_bf16_f32 v126, v126, v127
	v_cvt_pk_bf16_f32 v127, v128, v129
	v_cvt_pk_bf16_f32 v128, v122, v123
	v_cvt_pk_bf16_f32 v129, v124, v125
	global_store_dwordx4 v132, v[126:129], s[98:99]
	v_cvt_pk_bf16_f32 v118, v118, v119
	v_cvt_pk_bf16_f32 v119, v120, v121
	v_cvt_pk_bf16_f32 v120, v114, v115
	v_cvt_pk_bf16_f32 v121, v116, v117
	global_store_dwordx4 v132, v[118:121], s[98:99] offset:256
	v_add_u32_e32 v132, s20, v132
	v_cvt_pk_bf16_f32 v108, v108, v109
	v_cvt_pk_bf16_f32 v109, v110, v111
	v_cvt_pk_bf16_f32 v110, v104, v105
	v_cvt_pk_bf16_f32 v111, v106, v107
	global_store_dwordx4 v132, v[108:111], s[98:99]
	v_cvt_pk_bf16_f32 v100, v100, v101
	v_cvt_pk_bf16_f32 v101, v102, v103
	v_cvt_pk_bf16_f32 v102, v96, v97
	v_cvt_pk_bf16_f32 v103, v98, v99
	global_store_dwordx4 v132, v[100:103], s[98:99] offset:256
	v_add_u32_e32 v132, s20, v132
	v_cvt_pk_bf16_f32 v92, v92, v93
	v_cvt_pk_bf16_f32 v93, v94, v95
	v_cvt_pk_bf16_f32 v94, v88, v89
	v_cvt_pk_bf16_f32 v95, v90, v91
	global_store_dwordx4 v132, v[92:95], s[98:99]
	v_cvt_pk_bf16_f32 v84, v84, v85
	v_cvt_pk_bf16_f32 v85, v86, v87
	v_cvt_pk_bf16_f32 v86, v80, v81
	v_cvt_pk_bf16_f32 v87, v82, v83
	global_store_dwordx4 v132, v[84:87], s[98:99] offset:256
	v_add_u32_e32 v132, s20, v132
	v_cvt_pk_bf16_f32 v76, v76, v77
	v_cvt_pk_bf16_f32 v77, v78, v79
	v_cvt_pk_bf16_f32 v78, v72, v73
	v_cvt_pk_bf16_f32 v79, v74, v75
	global_store_dwordx4 v132, v[76:79], s[98:99]
	v_cvt_pk_bf16_f32 v68, v68, v69
	v_cvt_pk_bf16_f32 v69, v70, v71
	v_cvt_pk_bf16_f32 v70, v64, v65
	v_cvt_pk_bf16_f32 v71, v66, v67
	global_store_dwordx4 v132, v[68:71], s[98:99] offset:256
	v_add_u32_e32 v132, s21, v132
	v_cvt_pk_bf16_f32 v60, v60, v61
	v_cvt_pk_bf16_f32 v61, v62, v63
	v_cvt_pk_bf16_f32 v62, v56, v57
	v_cvt_pk_bf16_f32 v63, v58, v59
	global_store_dwordx4 v132, v[60:63], s[98:99]
	v_cvt_pk_bf16_f32 v52, v52, v53
	v_cvt_pk_bf16_f32 v53, v54, v55
	v_cvt_pk_bf16_f32 v54, v48, v49
	v_cvt_pk_bf16_f32 v55, v50, v51
	global_store_dwordx4 v132, v[52:55], s[98:99] offset:256
	v_add_u32_e32 v132, s20, v132
	v_cvt_pk_bf16_f32 v44, v44, v45
	v_cvt_pk_bf16_f32 v45, v46, v47
	v_cvt_pk_bf16_f32 v46, v40, v41
	v_cvt_pk_bf16_f32 v47, v42, v43
	global_store_dwordx4 v132, v[44:47], s[98:99]
	v_cvt_pk_bf16_f32 v36, v36, v37
	v_cvt_pk_bf16_f32 v37, v38, v39
	v_cvt_pk_bf16_f32 v38, v32, v33
	v_cvt_pk_bf16_f32 v39, v34, v35
	global_store_dwordx4 v132, v[36:39], s[98:99] offset:256
	v_add_u32_e32 v132, s20, v132
	v_cvt_pk_bf16_f32 v28, v28, v29
	v_cvt_pk_bf16_f32 v29, v30, v31
	v_cvt_pk_bf16_f32 v30, v24, v25
	v_cvt_pk_bf16_f32 v31, v26, v27
	global_store_dwordx4 v132, v[28:31], s[98:99]
	v_cvt_pk_bf16_f32 v20, v20, v21
	v_cvt_pk_bf16_f32 v21, v22, v23
	v_cvt_pk_bf16_f32 v22, v16, v17
	v_cvt_pk_bf16_f32 v23, v18, v19
	global_store_dwordx4 v132, v[20:23], s[98:99] offset:256
	v_add_u32_e32 v132, s20, v132
	v_cvt_pk_bf16_f32 v12, v12, v13
	v_cvt_pk_bf16_f32 v13, v14, v15
	v_cvt_pk_bf16_f32 v14, v8, v9
	v_cvt_pk_bf16_f32 v15, v10, v11
	global_store_dwordx4 v132, v[12:15], s[98:99]
	v_cvt_pk_bf16_f32 v4, v4, v5
	v_cvt_pk_bf16_f32 v5, v6, v7
	v_cvt_pk_bf16_f32 v6, v0, v1
	v_cvt_pk_bf16_f32 v7, v2, v3
	global_store_dwordx4 v132, v[4:7], s[98:99] offset:256
	s_nop 1
	v_readlane_b32 s20, v255, 61
	s_cmp_eq_u32 s20, 0
	s_cbranch_scc1 .Lepi_nb0
	v_writelane_b32 v255, 0, 61
	s_barrier
.Lepi_nb0:
	v_writelane_b32 v255, 1, 62
	s_branch .LBB0_837
.Lepi_relu2:
	v_or_b32_e32 v130, s78, v179
	v_lshl_add_u32 v130, s83, 8, v130
	s_lshl_b32 s20, s66, 8
	v_lshl_or_b32 v131, v178, 3, s20
	v_or_b32_e32 v131, s79, v131
	v_mul_lo_u32 v132, v130, s88
	v_add_lshl_u32 v132, v132, v131, 1
	s_lshl_b32 s20, s88, 5
	s_mul_i32 s21, s88, 0xa0
	s_mov_b64 s[98:99], s[90:91]
	v_lshlrev_b32_e32 v133, 2, v130
	global_load_dword v188, v133, s[96:97]
	global_load_dword v189, v133, s[96:97] offset:64
	global_load_dword v190, v133, s[96:97] offset:128
	global_load_dword v191, v133, s[96:97] offset:192
	global_load_dword v192, v133, s[96:97] offset:512
	global_load_dword v193, v133, s[96:97] offset:576
	global_load_dword v194, v133, s[96:97] offset:640
	global_load_dword v195, v133, s[96:97] offset:704
	s_waitcnt vmcnt(0)
	v_mov_b32_e32 v112, v188
	v_pk_mul_f32 v[126:127], v[126:127], v[112:113] op_sel_hi:[1,0]
	v_pk_mul_f32 v[128:129], v[128:129], v[112:113] op_sel_hi:[1,0]
	v_pk_mul_f32 v[122:123], v[122:123], v[112:113] op_sel_hi:[1,0]
	v_pk_mul_f32 v[124:125], v[124:125], v[112:113] op_sel_hi:[1,0]
	v_max_f32_e32 v126, 0, v126
	v_max_f32_e32 v127, 0, v127
	v_max_f32_e32 v128, 0, v128
	v_max_f32_e32 v129, 0, v129
	v_max_f32_e32 v122, 0, v122
	v_max_f32_e32 v123, 0, v123
	v_max_f32_e32 v124, 0, v124
	v_max_f32_e32 v125, 0, v125
	v_pk_mul_f32 v[126:127], v[126:127], v[126:127]
	v_pk_mul_f32 v[128:129], v[128:129], v[128:129]
	v_pk_mul_f32 v[122:123], v[122:123], v[122:123]
	v_pk_mul_f32 v[124:125], v[124:125], v[124:125]
	v_cvt_pk_bf16_f32 v126, v126, v127
	v_cvt_pk_bf16_f32 v127, v128, v129
	v_cvt_pk_bf16_f32 v128, v122, v123
	v_cvt_pk_bf16_f32 v129, v124, v125
	global_store_dwordx4 v132, v[126:129], s[98:99]
	v_pk_mul_f32 v[118:119], v[118:119], v[112:113] op_sel_hi:[1,0]
	v_pk_mul_f32 v[120:121], v[120:121], v[112:113] op_sel_hi:[1,0]
	v_pk_mul_f32 v[114:115], v[114:115], v[112:113] op_sel_hi:[1,0]
	v_pk_mul_f32 v[116:117], v[116:117], v[112:113] op_sel_hi:[1,0]
	v_max_f32_e32 v118, 0, v118
	v_max_f32_e32 v119, 0, v119
	v_max_f32_e32 v120, 0, v120
	v_max_f32_e32 v121, 0, v121
	v_max_f32_e32 v114, 0, v114
	v_max_f32_e32 v115, 0, v115
	v_max_f32_e32 v116, 0, v116
	v_max_f32_e32 v117, 0, v117
	v_pk_mul_f32 v[118:119], v[118:119], v[118:119]
; DI u32x4 pack8(f32x4 a, f32x4 b) { u32x4 w; w.x = cvtpk(a.x, a.y); w.y = cvtpk(a.z, a.w); w.z = cvtpk(b.x, b.y); w.w = cvtpk(b.z, b.w); return w; }
;   template <int MODE> DI void store8(int row, int col, f32x4 v0, f32x4 v1, int part) const {
;     if (MODE == EM_QKV || MODE == EM_RELU2 || MODE == EM_F32) { const float r_ = rs[row]; v0 *= r_; v1 *= r_; }
;     if (MODE == EM_TAIL) {
;       if (part >= 16) *(u32x4*)(O2 + ((size_t)(part - 16) * 1024 + (row - NPR)) * 2048 + col) = pack8(v0, v1);
;       else *(u32x4*)(O + (size_t)row * ldc + col) = pack8(v0, v1);
;     } else if (MODE == EM_SPLIT) {
;       bf16* d = (part & 1) ? O2 : O; *(u32x4*)(d + (size_t)row * ldc + col) = pack8(v0, v1);
;       if (part & 2) *(u32x4*)(O2 + (size_t)row * ldc + col) = (u32x4){0u, 0u, 0u, 0u};
;     } else if (MODE == EM_BF16) { *(u32x4*)(O + (size_t)row * ldc + col) = pack8(v0, v1); }
;     else if (MODE == EM_RELU2) {
;       f32x4 a = __builtin_elementwise_max(v0, (f32x4){0.f, 0.f, 0.f, 0.f}), b = __builtin_elementwise_max(v1, (f32x4){0.f, 0.f, 0.f, 0.f});
;       *(u32x4*)(O + (size_t)row * ldc + col) = pack8(a * a, b * b); }
	v_pk_mul_f32 v[120:121], v[120:121], v[120:121]
	v_pk_mul_f32 v[114:115], v[114:115], v[114:115]
	v_pk_mul_f32 v[116:117], v[116:117], v[116:117]
	v_cvt_pk_bf16_f32 v118, v118, v119
	v_cvt_pk_bf16_f32 v119, v120, v121
	v_cvt_pk_bf16_f32 v120, v114, v115
	v_cvt_pk_bf16_f32 v121, v116, v117
	global_store_dwordx4 v132, v[118:121], s[98:99] offset:256
	v_add_u32_e32 v132, s20, v132
	v_mov_b32_e32 v112, v189
	v_pk_mul_f32 v[108:109], v[108:109], v[112:113] op_sel_hi:[1,0]
	v_pk_mul_f32 v[110:111], v[110:111], v[112:113] op_sel_hi:[1,0]
	v_pk_mul_f32 v[104:105], v[104:105], v[112:113] op_sel_hi:[1,0]
	v_pk_mul_f32 v[106:107], v[106:107], v[112:113] op_sel_hi:[1,0]
	v_max_f32_e32 v108, 0, v108
	v_max_f32_e32 v109, 0, v109
	v_max_f32_e32 v110, 0, v110
	v_max_f32_e32 v111, 0, v111
	v_max_f32_e32 v104, 0, v104
	v_max_f32_e32 v105, 0, v105
	v_max_f32_e32 v106, 0, v106
	v_max_f32_e32 v107, 0, v107
	v_pk_mul_f32 v[108:109], v[108:109], v[108:109]
	v_pk_mul_f32 v[110:111], v[110:111], v[110:111]
	v_pk_mul_f32 v[104:105], v[104:105], v[104:105]
	v_pk_mul_f32 v[106:107], v[106:107], v[106:107]
	v_cvt_pk_bf16_f32 v108, v108, v109
	v_cvt_pk_bf16_f32 v109, v110, v111
	v_cvt_pk_bf16_f32 v110, v104, v105
	v_cvt_pk_bf16_f32 v111, v106, v107
	global_store_dwordx4 v132, v[108:111], s[98:99]
	v_pk_mul_f32 v[100:101], v[100:101], v[112:113] op_sel_hi:[1,0]
	v_pk_mul_f32 v[102:103], v[102:103], v[112:113] op_sel_hi:[1,0]
	v_pk_mul_f32 v[96:97], v[96:97], v[112:113] op_sel_hi:[1,0]
	v_pk_mul_f32 v[98:99], v[98:99], v[112:113] op_sel_hi:[1,0]
	v_max_f32_e32 v100, 0, v100
	v_max_f32_e32 v101, 0, v101
	v_max_f32_e32 v102, 0, v102
	v_max_f32_e32 v103, 0, v103
	v_max_f32_e32 v96, 0, v96
	v_max_f32_e32 v97, 0, v97
	v_max_f32_e32 v98, 0, v98
	v_max_f32_e32 v99, 0, v99
	v_pk_mul_f32 v[100:101], v[100:101], v[100:101]
	v_pk_mul_f32 v[102:103], v[102:103], v[102:103]
	v_pk_mul_f32 v[96:97], v[96:97], v[96:97]
	v_pk_mul_f32 v[98:99], v[98:99], v[98:99]
	v_cvt_pk_bf16_f32 v100, v100, v101
	v_cvt_pk_bf16_f32 v101, v102, v103
	v_cvt_pk_bf16_f32 v102, v96, v97
	v_cvt_pk_bf16_f32 v103, v98, v99
	global_store_dwordx4 v132, v[100:103], s[98:99] offset:256
	v_add_u32_e32 v132, s20, v132
	v_mov_b32_e32 v112, v190
	v_pk_mul_f32 v[92:93], v[92:93], v[112:113] op_sel_hi:[1,0]
	v_pk_mul_f32 v[94:95], v[94:95], v[112:113] op_sel_hi:[1,0]
	v_pk_mul_f32 v[88:89], v[88:89], v[112:113] op_sel_hi:[1,0]
	v_pk_mul_f32 v[90:91], v[90:91], v[112:113] op_sel_hi:[1,0]
	v_max_f32_e32 v92, 0, v92
	v_max_f32_e32 v93, 0, v93
	v_max_f32_e32 v94, 0, v94
	v_max_f32_e32 v95, 0, v95
	v_max_f32_e32 v88, 0, v88
	v_max_f32_e32 v89, 0, v89
	v_max_f32_e32 v90, 0, v90
	v_max_f32_e32 v91, 0, v91
	v_pk_mul_f32 v[92:93], v[92:93], v[92:93]
	v_pk_mul_f32 v[94:95], v[94:95], v[94:95]
	v_pk_mul_f32 v[88:89], v[88:89], v[88:89]
	v_pk_mul_f32 v[90:91], v[90:91], v[90:91]
	v_cvt_pk_bf16_f32 v92, v92, v93
	v_cvt_pk_bf16_f32 v93, v94, v95
	v_cvt_pk_bf16_f32 v94, v88, v89
	v_cvt_pk_bf16_f32 v95, v90, v91
	global_store_dwordx4 v132, v[92:95], s[98:99]
	v_pk_mul_f32 v[84:85], v[84:85], v[112:113] op_sel_hi:[1,0]
	v_pk_mul_f32 v[86:87], v[86:87], v[112:113] op_sel_hi:[1,0]
	v_pk_mul_f32 v[80:81], v[80:81], v[112:113] op_sel_hi:[1,0]
	v_pk_mul_f32 v[82:83], v[82:83], v[112:113] op_sel_hi:[1,0]
	v_max_f32_e32 v84, 0, v84
	v_max_f32_e32 v85, 0, v85
	v_max_f32_e32 v86, 0, v86
	v_max_f32_e32 v87, 0, v87
	v_max_f32_e32 v80, 0, v80
	v_max_f32_e32 v81, 0, v81
	v_max_f32_e32 v82, 0, v82
	v_max_f32_e32 v83, 0, v83
	v_pk_mul_f32 v[84:85], v[84:85], v[84:85]
	v_pk_mul_f32 v[86:87], v[86:87], v[86:87]
	v_pk_mul_f32 v[80:81], v[80:81], v[80:81]
	v_pk_mul_f32 v[82:83], v[82:83], v[82:83]
	v_cvt_pk_bf16_f32 v84, v84, v85
	v_cvt_pk_bf16_f32 v85, v86, v87
	v_cvt_pk_bf16_f32 v86, v80, v81
	v_cvt_pk_bf16_f32 v87, v82, v83
	global_store_dwordx4 v132, v[84:87], s[98:99] offset:256
	v_add_u32_e32 v132, s20, v132
	v_mov_b32_e32 v112, v191
	v_pk_mul_f32 v[76:77], v[76:77], v[112:113] op_sel_hi:[1,0]
	v_pk_mul_f32 v[78:79], v[78:79], v[112:113] op_sel_hi:[1,0]
	v_pk_mul_f32 v[72:73], v[72:73], v[112:113] op_sel_hi:[1,0]
	v_pk_mul_f32 v[74:75], v[74:75], v[112:113] op_sel_hi:[1,0]
	v_max_f32_e32 v76, 0, v76
	v_max_f32_e32 v77, 0, v77
	v_max_f32_e32 v78, 0, v78
	v_max_f32_e32 v79, 0, v79
	v_max_f32_e32 v72, 0, v72
	v_max_f32_e32 v73, 0, v73
	v_max_f32_e32 v74, 0, v74
	v_max_f32_e32 v75, 0, v75
	v_pk_mul_f32 v[76:77], v[76:77], v[76:77]
	v_pk_mul_f32 v[78:79], v[78:79], v[78:79]
	v_pk_mul_f32 v[72:73], v[72:73], v[72:73]
	v_pk_mul_f32 v[74:75], v[74:75], v[74:75]
	v_cvt_pk_bf16_f32 v76, v76, v77
	v_cvt_pk_bf16_f32 v77, v78, v79
	v_cvt_pk_bf16_f32 v78, v72, v73
	v_cvt_pk_bf16_f32 v79, v74, v75
	global_store_dwordx4 v132, v[76:79], s[98:99]
	v_pk_mul_f32 v[68:69], v[68:69], v[112:113] op_sel_hi:[1,0]
	v_pk_mul_f32 v[70:71], v[70:71], v[112:113] op_sel_hi:[1,0]
	v_pk_mul_f32 v[64:65], v[64:65], v[112:113] op_sel_hi:[1,0]
	v_pk_mul_f32 v[66:67], v[66:67], v[112:113] op_sel_hi:[1,0]
	v_max_f32_e32 v68, 0, v68
	v_max_f32_e32 v69, 0, v69
	v_max_f32_e32 v70, 0, v70
	v_max_f32_e32 v71, 0, v71
	v_max_f32_e32 v64, 0, v64
	v_max_f32_e32 v65, 0, v65
	v_max_f32_e32 v66, 0, v66
	v_max_f32_e32 v67, 0, v67
	v_pk_mul_f32 v[68:69], v[68:69], v[68:69]
	v_pk_mul_f32 v[70:71], v[70:71], v[70:71]
	v_pk_mul_f32 v[64:65], v[64:65], v[64:65]
	v_pk_mul_f32 v[66:67], v[66:67], v[66:67]
	v_cvt_pk_bf16_f32 v68, v68, v69
	v_cvt_pk_bf16_f32 v69, v70, v71
	v_cvt_pk_bf16_f32 v70, v64, v65
	v_cvt_pk_bf16_f32 v71, v66, v67
	global_store_dwordx4 v132, v[68:71], s[98:99] offset:256
	v_add_u32_e32 v132, s21, v132
	v_mov_b32_e32 v112, v192
	v_pk_mul_f32 v[60:61], v[60:61], v[112:113] op_sel_hi:[1,0]
; #define PG8_BAR __builtin_amdgcn_s_barrier()
; DI u32x4 pack8(f32x4 a, f32x4 b) { u32x4 w; w.x = cvtpk(a.x, a.y); w.y = cvtpk(a.z, a.w); w.z = cvtpk(b.x, b.y); w.w = cvtpk(b.z, b.w); return w; }
; template <class Epi, class Sched, bool ALIGN_EPI = false, bool SP2 = false>
; __device__ __forceinline__ void gemm_phase(PG8_LAS unsigned char* lds, const Gemm g, const Sched& S, const Epi& E) {
;     ...
;         if constexpr (ALIGN_EPI) { if (wr == 0) PG8_BAR; }
;   template <int MODE> DI void store8(int row, int col, f32x4 v0, f32x4 v1, int part) const {
;     if (MODE == EM_QKV || MODE == EM_RELU2 || MODE == EM_F32) { const float r_ = rs[row]; v0 *= r_; v1 *= r_; }
;     if (MODE == EM_TAIL) {
;       if (part >= 16) *(u32x4*)(O2 + ((size_t)(part - 16) * 1024 + (row - NPR)) * 2048 + col) = pack8(v0, v1);
;       else *(u32x4*)(O + (size_t)row * ldc + col) = pack8(v0, v1);
;     } else if (MODE == EM_SPLIT) {
;       bf16* d = (part & 1) ? O2 : O; *(u32x4*)(d + (size_t)row * ldc + col) = pack8(v0, v1);
;       if (part & 2) *(u32x4*)(O2 + (size_t)row * ldc + col) = (u32x4){0u, 0u, 0u, 0u};
;     } else if (MODE == EM_BF16) { *(u32x4*)(O + (size_t)row * ldc + col) = pack8(v0, v1); }
;     else if (MODE == EM_RELU2) {
;       f32x4 a = __builtin_elementwise_max(v0, (f32x4){0.f, 0.f, 0.f, 0.f}), b = __builtin_elementwise_max(v1, (f32x4){0.f, 0.f, 0.f, 0.f});
;       *(u32x4*)(O + (size_t)row * ldc + col) = pack8(a * a, b * b); }
	v_pk_mul_f32 v[62:63], v[62:63], v[112:113] op_sel_hi:[1,0]
	v_pk_mul_f32 v[56:57], v[56:57], v[112:113] op_sel_hi:[1,0]
	v_pk_mul_f32 v[58:59], v[58:59], v[112:113] op_sel_hi:[1,0]
	v_max_f32_e32 v60, 0, v60
	v_max_f32_e32 v61, 0, v61
	v_max_f32_e32 v62, 0, v62
	v_max_f32_e32 v63, 0, v63
	v_max_f32_e32 v56, 0, v56
	v_max_f32_e32 v57, 0, v57
	v_max_f32_e32 v58, 0, v58
	v_max_f32_e32 v59, 0, v59
	v_pk_mul_f32 v[60:61], v[60:61], v[60:61]
	v_pk_mul_f32 v[62:63], v[62:63], v[62:63]
	v_pk_mul_f32 v[56:57], v[56:57], v[56:57]
	v_pk_mul_f32 v[58:59], v[58:59], v[58:59]
	v_cvt_pk_bf16_f32 v60, v60, v61
	v_cvt_pk_bf16_f32 v61, v62, v63
	v_cvt_pk_bf16_f32 v62, v56, v57
	v_cvt_pk_bf16_f32 v63, v58, v59
	global_store_dwordx4 v132, v[60:63], s[98:99]
	v_pk_mul_f32 v[52:53], v[52:53], v[112:113] op_sel_hi:[1,0]
	v_pk_mul_f32 v[54:55], v[54:55], v[112:113] op_sel_hi:[1,0]
	v_pk_mul_f32 v[48:49], v[48:49], v[112:113] op_sel_hi:[1,0]
	v_pk_mul_f32 v[50:51], v[50:51], v[112:113] op_sel_hi:[1,0]
	v_max_f32_e32 v52, 0, v52
	v_max_f32_e32 v53, 0, v53
	v_max_f32_e32 v54, 0, v54
	v_max_f32_e32 v55, 0, v55
	v_max_f32_e32 v48, 0, v48
	v_max_f32_e32 v49, 0, v49
	v_max_f32_e32 v50, 0, v50
	v_max_f32_e32 v51, 0, v51
	v_pk_mul_f32 v[52:53], v[52:53], v[52:53]
	v_pk_mul_f32 v[54:55], v[54:55], v[54:55]
	v_pk_mul_f32 v[48:49], v[48:49], v[48:49]
	v_pk_mul_f32 v[50:51], v[50:51], v[50:51]
	v_cvt_pk_bf16_f32 v52, v52, v53
	v_cvt_pk_bf16_f32 v53, v54, v55
	v_cvt_pk_bf16_f32 v54, v48, v49
	v_cvt_pk_bf16_f32 v55, v50, v51
	global_store_dwordx4 v132, v[52:55], s[98:99] offset:256
	v_add_u32_e32 v132, s20, v132
	v_mov_b32_e32 v112, v193
	v_pk_mul_f32 v[44:45], v[44:45], v[112:113] op_sel_hi:[1,0]
	v_pk_mul_f32 v[46:47], v[46:47], v[112:113] op_sel_hi:[1,0]
	v_pk_mul_f32 v[40:41], v[40:41], v[112:113] op_sel_hi:[1,0]
	v_pk_mul_f32 v[42:43], v[42:43], v[112:113] op_sel_hi:[1,0]
	v_max_f32_e32 v44, 0, v44
	v_max_f32_e32 v45, 0, v45
	v_max_f32_e32 v46, 0, v46
	v_max_f32_e32 v47, 0, v47
	v_max_f32_e32 v40, 0, v40
	v_max_f32_e32 v41, 0, v41
	v_max_f32_e32 v42, 0, v42
	v_max_f32_e32 v43, 0, v43
	v_pk_mul_f32 v[44:45], v[44:45], v[44:45]
	v_pk_mul_f32 v[46:47], v[46:47], v[46:47]
	v_pk_mul_f32 v[40:41], v[40:41], v[40:41]
	v_pk_mul_f32 v[42:43], v[42:43], v[42:43]
	v_cvt_pk_bf16_f32 v44, v44, v45
	v_cvt_pk_bf16_f32 v45, v46, v47
	v_cvt_pk_bf16_f32 v46, v40, v41
	v_cvt_pk_bf16_f32 v47, v42, v43
	global_store_dwordx4 v132, v[44:47], s[98:99]
	v_pk_mul_f32 v[36:37], v[36:37], v[112:113] op_sel_hi:[1,0]
	v_pk_mul_f32 v[38:39], v[38:39], v[112:113] op_sel_hi:[1,0]
	v_pk_mul_f32 v[32:33], v[32:33], v[112:113] op_sel_hi:[1,0]
	v_pk_mul_f32 v[34:35], v[34:35], v[112:113] op_sel_hi:[1,0]
	v_max_f32_e32 v36, 0, v36
	v_max_f32_e32 v37, 0, v37
	v_max_f32_e32 v38, 0, v38
	v_max_f32_e32 v39, 0, v39
	v_max_f32_e32 v32, 0, v32
	v_max_f32_e32 v33, 0, v33
	v_max_f32_e32 v34, 0, v34
	v_max_f32_e32 v35, 0, v35
	v_pk_mul_f32 v[36:37], v[36:37], v[36:37]
	v_pk_mul_f32 v[38:39], v[38:39], v[38:39]
	v_pk_mul_f32 v[32:33], v[32:33], v[32:33]
	v_pk_mul_f32 v[34:35], v[34:35], v[34:35]
	v_cvt_pk_bf16_f32 v36, v36, v37
	v_cvt_pk_bf16_f32 v37, v38, v39
	v_cvt_pk_bf16_f32 v38, v32, v33
	v_cvt_pk_bf16_f32 v39, v34, v35
	global_store_dwordx4 v132, v[36:39], s[98:99] offset:256
	v_add_u32_e32 v132, s20, v132
	v_mov_b32_e32 v112, v194
	v_pk_mul_f32 v[28:29], v[28:29], v[112:113] op_sel_hi:[1,0]
	v_pk_mul_f32 v[30:31], v[30:31], v[112:113] op_sel_hi:[1,0]
	v_pk_mul_f32 v[24:25], v[24:25], v[112:113] op_sel_hi:[1,0]
	v_pk_mul_f32 v[26:27], v[26:27], v[112:113] op_sel_hi:[1,0]
	v_max_f32_e32 v28, 0, v28
	v_max_f32_e32 v29, 0, v29
	v_max_f32_e32 v30, 0, v30
	v_max_f32_e32 v31, 0, v31
	v_max_f32_e32 v24, 0, v24
	v_max_f32_e32 v25, 0, v25
	v_max_f32_e32 v26, 0, v26
	v_max_f32_e32 v27, 0, v27
	v_pk_mul_f32 v[28:29], v[28:29], v[28:29]
	v_pk_mul_f32 v[30:31], v[30:31], v[30:31]
	v_pk_mul_f32 v[24:25], v[24:25], v[24:25]
	v_pk_mul_f32 v[26:27], v[26:27], v[26:27]
	v_cvt_pk_bf16_f32 v28, v28, v29
	v_cvt_pk_bf16_f32 v29, v30, v31
	v_cvt_pk_bf16_f32 v30, v24, v25
	v_cvt_pk_bf16_f32 v31, v26, v27
	global_store_dwordx4 v132, v[28:31], s[98:99]
	v_pk_mul_f32 v[20:21], v[20:21], v[112:113] op_sel_hi:[1,0]
	v_pk_mul_f32 v[22:23], v[22:23], v[112:113] op_sel_hi:[1,0]
	v_pk_mul_f32 v[16:17], v[16:17], v[112:113] op_sel_hi:[1,0]
	v_pk_mul_f32 v[18:19], v[18:19], v[112:113] op_sel_hi:[1,0]
	v_max_f32_e32 v20, 0, v20
	v_max_f32_e32 v21, 0, v21
	v_max_f32_e32 v22, 0, v22
	v_max_f32_e32 v23, 0, v23
	v_max_f32_e32 v16, 0, v16
	v_max_f32_e32 v17, 0, v17
	v_max_f32_e32 v18, 0, v18
	v_max_f32_e32 v19, 0, v19
	v_pk_mul_f32 v[20:21], v[20:21], v[20:21]
	v_pk_mul_f32 v[22:23], v[22:23], v[22:23]
	v_pk_mul_f32 v[16:17], v[16:17], v[16:17]
	v_pk_mul_f32 v[18:19], v[18:19], v[18:19]
	v_cvt_pk_bf16_f32 v20, v20, v21
	v_cvt_pk_bf16_f32 v21, v22, v23
	v_cvt_pk_bf16_f32 v22, v16, v17
	v_cvt_pk_bf16_f32 v23, v18, v19
	global_store_dwordx4 v132, v[20:23], s[98:99] offset:256
	v_add_u32_e32 v132, s20, v132
	v_mov_b32_e32 v112, v195
	v_pk_mul_f32 v[12:13], v[12:13], v[112:113] op_sel_hi:[1,0]
	v_pk_mul_f32 v[14:15], v[14:15], v[112:113] op_sel_hi:[1,0]
	v_pk_mul_f32 v[8:9], v[8:9], v[112:113] op_sel_hi:[1,0]
	v_pk_mul_f32 v[10:11], v[10:11], v[112:113] op_sel_hi:[1,0]
	v_max_f32_e32 v12, 0, v12
	v_max_f32_e32 v13, 0, v13
	v_max_f32_e32 v14, 0, v14
	v_max_f32_e32 v15, 0, v15
	v_max_f32_e32 v8, 0, v8
	v_max_f32_e32 v9, 0, v9
	v_max_f32_e32 v10, 0, v10
	v_max_f32_e32 v11, 0, v11
	v_pk_mul_f32 v[12:13], v[12:13], v[12:13]
	v_pk_mul_f32 v[14:15], v[14:15], v[14:15]
	v_pk_mul_f32 v[8:9], v[8:9], v[8:9]
	v_pk_mul_f32 v[10:11], v[10:11], v[10:11]
	v_cvt_pk_bf16_f32 v12, v12, v13
	v_cvt_pk_bf16_f32 v13, v14, v15
	v_cvt_pk_bf16_f32 v14, v8, v9
	v_cvt_pk_bf16_f32 v15, v10, v11
	global_store_dwordx4 v132, v[12:15], s[98:99]
	v_pk_mul_f32 v[4:5], v[4:5], v[112:113] op_sel_hi:[1,0]
	v_pk_mul_f32 v[6:7], v[6:7], v[112:113] op_sel_hi:[1,0]
	v_pk_mul_f32 v[0:1], v[0:1], v[112:113] op_sel_hi:[1,0]
	v_pk_mul_f32 v[2:3], v[2:3], v[112:113] op_sel_hi:[1,0]
	v_max_f32_e32 v4, 0, v4
	v_max_f32_e32 v5, 0, v5
	v_max_f32_e32 v6, 0, v6
	v_max_f32_e32 v7, 0, v7
	v_max_f32_e32 v0, 0, v0
	v_max_f32_e32 v1, 0, v1
	v_max_f32_e32 v2, 0, v2
	v_max_f32_e32 v3, 0, v3
	v_pk_mul_f32 v[4:5], v[4:5], v[4:5]
	v_pk_mul_f32 v[6:7], v[6:7], v[6:7]
	v_pk_mul_f32 v[0:1], v[0:1], v[0:1]
	v_pk_mul_f32 v[2:3], v[2:3], v[2:3]
	v_cvt_pk_bf16_f32 v4, v4, v5
	v_cvt_pk_bf16_f32 v5, v6, v7
	v_cvt_pk_bf16_f32 v6, v0, v1
	v_cvt_pk_bf16_f32 v7, v2, v3
	global_store_dwordx4 v132, v[4:7], s[98:99] offset:256
	s_nop 1
	v_readlane_b32 s20, v255, 61
	s_cmp_eq_u32 s20, 0
	s_cbranch_scc1 .Lepi_nb1
	v_writelane_b32 v255, 0, 61
	s_barrier
